# rwkv_prep kk-norm pass: 16 parameter loads issued up front with counted waits; scan staging 1-x via one packed fma
# speedup vs baseline: 1.0034x; 1.0034x over previous
; DI float bflo(unsigned u) { return __uint_as_float(u << 16); }
; DI float bfhi(unsigned u) { return __uint_as_float(u & 0xffff0000u); }
; DI void rwkv_prep(const Params& p, int l, int item, char* smraw) {
;     ...
;     float ss = 0.f;
; #pragma unroll
;     for (int nt = 0; nt < 2; ++nt)
; #pragma unroll
;       for (int q = 0; q < 4; ++q) {
;         const int c = w * 64 + 32 * nt + 8 * q + 4 * h;
;         const uint2 zk = *(const uint2*)(SR + (tokl + 1) * 776 + 256 + c);
;         const uint2 pk_ = *(const uint2*)(SR + tokl * 776 + 256 + c);
;         const float4 muk = *(const float4*)(mu + 256 + c);
;         const float4 kw4 = *(const float4*)(kkw + c);
;         float x0 = bflo(zk.x), x1 = bfhi(zk.x), x2 = bflo(zk.y), x3 = bfhi(zk.y);
;         x0 = (x0 + (bflo(pk_.x) - x0) * muk.x) * kw4.x; x1 = (x1 + (bfhi(pk_.x) - x1) * muk.y) * kw4.y;
;         x2 = (x2 + (bflo(pk_.y) - x2) * muk.z) * kw4.z; x3 = (x3 + (bfhi(pk_.y) - x3) * muk.w) * kw4.w;
;         ss += x0 * x0 + x1 * x1 + x2 * x2 + x3 * x3;
;       }
.LBB0_390:
	s_or_b64 exec, exec, s[4:5]
	v_readlane_b32 s0, v252, 6
	v_readlane_b32 s1, v252, 7
	s_mov_b64 s[4:5], s[0:1]
	s_waitcnt lgkmcnt(0)
	s_barrier
	s_load_dwordx2 s[58:59], s[4:5], 0xf0
	s_mov_b64 s[4:5], s[0:1]
	s_load_dwordx2 s[60:61], s[4:5], 0xf0
	s_mov_b64 s[4:5], s[0:1]
	s_load_dwordx2 s[56:57], s[4:5], 0xf0
	s_mov_b64 s[4:5], s[0:1]
	s_load_dwordx2 s[54:55], s[4:5], 0xf0
	s_mov_b64 s[4:5], s[0:1]
	s_load_dwordx2 s[46:47], s[4:5], 0x60
	s_mov_b64 s[4:5], s[0:1]
	s_load_dwordx2 s[36:37], s[4:5], 0x70
	s_mov_b64 s[4:5], s[0:1]
	s_load_dwordx2 s[4:5], s[4:5], 0x80
	v_ashrrev_i32_e32 v0, 3, v54
	v_bfe_u32 v118, v54, 5, 1
	v_bfe_u32 v87, v54, 6, 2
	v_lshlrev_b32_e32 v119, 2, v118
	s_waitcnt lgkmcnt(0)
	s_add_u32 s40, s4, s34
	s_addc_u32 s41, s5, s35
	s_mov_b64 s[4:5], s[0:1]
	s_load_dwordx2 s[50:51], s[4:5], 0x88
	s_mov_b64 s[4:5], s[0:1]
	s_load_dwordx2 s[52:53], s[4:5], 0x90
	s_mov_b64 s[4:5], s[0:1]
	s_load_dwordx2 s[44:45], s[4:5], 0xa8
	s_mov_b64 s[4:5], s[0:1]
	s_load_dwordx2 s[62:63], s[4:5], 0xf0
	s_mov_b64 s[4:5], s[0:1]
	s_load_dwordx2 s[64:65], s[4:5], 0xf0
	s_mov_b64 s[4:5], s[0:1]
	s_movk_i32 s0, 0xffe0
	s_waitcnt vmcnt(0)
	v_bfi_b32 v19, s0, v0, v54
	s_movk_i32 s0, 0x610
	v_mul_lo_u32 v0, v19, s0
	v_lshl_or_b32 v120, v87, 6, v119
	v_add_u32_e32 v121, 0, v0
	v_lshl_add_u32 v0, v120, 1, v121
	v_add_u32_e32 v10, 0xd000, v0
	v_add_u32_e32 v11, 0xc800, v0
	v_lshlrev_b32_e32 v0, 2, v120
	s_load_dwordx2 s[42:43], s[4:5], 0xf0
	ds_read2_b64 v[6:9], v10 offset0:130 offset1:132
	ds_read2_b64 v[12:15], v11 offset0:192 offset1:194
	ds_read2_b64 v[2:5], v11 offset0:196 offset1:198
	global_load_dwordx4 v[128:131], v0, s[38:39] offset:1024
	global_load_dwordx4 v[132:135], v0, s[40:41]
	global_load_dwordx4 v[136:139], v0, s[38:39] offset:1056
	global_load_dwordx4 v[140:143], v0, s[40:41] offset:32
	global_load_dwordx4 v[144:147], v0, s[38:39] offset:1088
	global_load_dwordx4 v[148:151], v0, s[40:41] offset:64
	global_load_dwordx4 v[152:155], v0, s[38:39] offset:1120
	global_load_dwordx4 v[156:159], v0, s[40:41] offset:96
	global_load_dwordx4 v[160:163], v0, s[38:39] offset:1152
	global_load_dwordx4 v[164:167], v0, s[40:41] offset:128
	global_load_dwordx4 v[168:171], v0, s[38:39] offset:1184
	global_load_dwordx4 v[172:175], v0, s[40:41] offset:160
	global_load_dwordx4 v[176:179], v0, s[38:39] offset:1216
	global_load_dwordx4 v[180:183], v0, s[40:41] offset:192
	global_load_dwordx4 v[184:187], v0, s[38:39] offset:1248
	global_load_dwordx4 v[188:191], v0, s[40:41] offset:224
	s_mov_b32 s0, 0xf800000
	s_add_u32 s46, s46, s34
	s_waitcnt lgkmcnt(0)
	v_lshlrev_b32_e32 v16, 16, v6
	v_and_b32_e32 v6, 0xffff0000, v6
	v_lshlrev_b32_e32 v28, 16, v12
	v_and_b32_e32 v12, 0xffff0000, v12
	v_sub_f32_e32 v12, v12, v6
	v_lshlrev_b32_e32 v17, 16, v7
	v_and_b32_e32 v7, 0xffff0000, v7
	v_sub_f32_e32 v28, v28, v16
	s_addc_u32 s47, s47, s35
	s_add_u32 s48, s36, s34
	s_addc_u32 s49, s37, s35
	v_add_u32_e32 v82, s10, v19
	v_ashrrev_i32_e32 v83, 31, v82
	v_and_b32_e32 v18, 31, v54
	s_add_u32 s50, s50, s34
	s_addc_u32 s51, s51, s35
	s_add_u32 s52, s52, s34
	s_addc_u32 s53, s53, s35
	v_mov_b32_e32 v122, 0
	s_waitcnt vmcnt(15)
	v_fmac_f32_e32 v6, v12, v129
	v_lshlrev_b32_e32 v12, 16, v13
	v_and_b32_e32 v13, 0xffff0000, v13
	v_sub_f32_e32 v12, v12, v17
	v_sub_f32_e32 v13, v13, v7
	v_fmac_f32_e32 v16, v128, v28
	v_fmac_f32_e32 v17, v12, v130
	v_fmac_f32_e32 v7, v13, v131
	s_waitcnt vmcnt(14)
	v_mul_f32_e32 v16, v16, v132
	v_mul_f32_e32 v6, v6, v133
	v_mul_f32_e32 v12, v17, v134
	v_mul_f32_e32 v7, v7, v135
	v_mul_f32_e32 v6, v6, v6
	v_fmac_f32_e32 v6, v16, v16
	v_fmac_f32_e32 v6, v12, v12
	v_fmac_f32_e32 v6, v7, v7
	v_lshlrev_b32_e32 v7, 16, v8
	v_lshlrev_b32_e32 v13, 16, v14
	v_sub_f32_e32 v13, v13, v7
	v_and_b32_e32 v8, 0xffff0000, v8
	v_lshlrev_b32_e32 v12, 16, v9
	v_and_b32_e32 v9, 0xffff0000, v9
	s_waitcnt vmcnt(13)
	v_fmac_f32_e32 v7, v136, v13
	v_and_b32_e32 v13, 0xffff0000, v14
	v_sub_f32_e32 v13, v13, v8
	v_fmac_f32_e32 v8, v13, v137
	v_lshlrev_b32_e32 v13, 16, v15
	v_sub_f32_e32 v13, v13, v12
	s_waitcnt vmcnt(12)
	v_mul_f32_e32 v8, v8, v141
	v_fmac_f32_e32 v12, v13, v138
	v_and_b32_e32 v13, 0xffff0000, v15
	v_mul_f32_e32 v7, v7, v140
	v_sub_f32_e32 v13, v13, v9
	v_mul_f32_e32 v8, v8, v8
	v_mul_f32_e32 v12, v12, v142
	v_fmac_f32_e32 v9, v13, v139
	v_fmac_f32_e32 v8, v7, v7
	v_mul_f32_e32 v9, v9, v143
	v_fmac_f32_e32 v8, v12, v12
	v_fmac_f32_e32 v8, v9, v9
	v_add_f32_e32 v16, v6, v8
	ds_read2_b64 v[6:9], v10 offset0:134 offset1:136
	v_lshlrev_b32_e32 v25, 16, v2
	v_and_b32_e32 v2, 0xffff0000, v2
	s_waitcnt lgkmcnt(0)
	v_lshlrev_b32_e32 v17, 16, v6
	v_and_b32_e32 v6, 0xffff0000, v6
	v_sub_f32_e32 v2, v2, v6
	v_lshlrev_b32_e32 v24, 16, v7
	v_and_b32_e32 v7, 0xffff0000, v7
	v_sub_f32_e32 v25, v25, v17
	s_waitcnt vmcnt(11)
	v_fmac_f32_e32 v6, v2, v145
	s_waitcnt vmcnt(10)
	v_mul_f32_e32 v2, v6, v149
	v_lshlrev_b32_e32 v6, 16, v3
	v_and_b32_e32 v3, 0xffff0000, v3
	v_fmac_f32_e32 v17, v144, v25
	v_sub_f32_e32 v6, v6, v24
	v_sub_f32_e32 v3, v3, v7
	v_mul_f32_e32 v12, v17, v148
	v_fmac_f32_e32 v24, v6, v146
	v_fmac_f32_e32 v7, v3, v147
	v_mul_f32_e32 v2, v2, v2
	v_mul_f32_e32 v6, v24, v150
	v_mul_f32_e32 v3, v7, v151
	v_fmac_f32_e32 v2, v12, v12
	v_fmac_f32_e32 v2, v6, v6
	v_fmac_f32_e32 v2, v3, v3
	v_lshlrev_b32_e32 v3, 16, v8
	v_and_b32_e32 v6, 0xffff0000, v8
	v_lshlrev_b32_e32 v7, 16, v9
	v_and_b32_e32 v8, 0xffff0000, v9
	v_lshlrev_b32_e32 v9, 16, v4
	v_and_b32_e32 v4, 0xffff0000, v4
	v_sub_f32_e32 v4, v4, v6
	v_sub_f32_e32 v9, v9, v3
	v_add_f32_e32 v2, v16, v2
	s_waitcnt vmcnt(9)
	v_fmac_f32_e32 v6, v4, v153
	s_waitcnt vmcnt(8)
; DI float bflo(unsigned u) { return __uint_as_float(u << 16); }
; DI float bfhi(unsigned u) { return __uint_as_float(u & 0xffff0000u); }
; DI float xor32_sum(float x) { auto r = __builtin_amdgcn_permlane32_swap(__float_as_uint(x), __float_as_uint(x), false, false); return __uint_as_float(r[0]) + __uint_as_float(r[1]); }
; DI void rwkv_prep(const Params& p, int l, int item, char* smraw) {
;     ...
;         const uint2 zk = *(const uint2*)(SR + (tokl + 1) * 776 + 256 + c);
;         const uint2 pk_ = *(const uint2*)(SR + tokl * 776 + 256 + c);
;         const float4 muk = *(const float4*)(mu + 256 + c);
;         const float4 kw4 = *(const float4*)(kkw + c);
;         float x0 = bflo(zk.x), x1 = bfhi(zk.x), x2 = bflo(zk.y), x3 = bfhi(zk.y);
;         x0 = (x0 + (bflo(pk_.x) - x0) * muk.x) * kw4.x; x1 = (x1 + (bfhi(pk_.x) - x1) * muk.y) * kw4.y;
;         x2 = (x2 + (bflo(pk_.y) - x2) * muk.z) * kw4.z; x3 = (x3 + (bfhi(pk_.y) - x3) * muk.w) * kw4.w;
;         ss += x0 * x0 + x1 * x1 + x2 * x2 + x3 * x3;
;       }
;     ss = xor32_sum(ss);
;     const float inv = 1.f / fmaxf(sqrtf(ss), 1e-12f);
;     float bsum = 0.f;
;     bf16_t* prow = pr + ((size_t)((b * 4 + w) * 2048 + t)) * 384;
	v_mul_f32_e32 v4, v6, v157
	v_lshlrev_b32_e32 v6, 16, v5
	v_fmac_f32_e32 v3, v152, v9
	v_sub_f32_e32 v6, v6, v7
	v_and_b32_e32 v5, 0xffff0000, v5
	v_mul_f32_e32 v3, v3, v156
	v_fmac_f32_e32 v7, v6, v154
	v_sub_f32_e32 v5, v5, v8
	v_mul_f32_e32 v4, v4, v4
	v_mul_f32_e32 v6, v7, v158
	v_fmac_f32_e32 v8, v5, v155
	v_fmac_f32_e32 v4, v3, v3
	v_mul_f32_e32 v5, v8, v159
	v_fmac_f32_e32 v4, v6, v6
	v_fmac_f32_e32 v4, v5, v5
	v_add_f32_e32 v16, v2, v4
	ds_read2_b64 v[6:9], v10 offset0:138 offset1:140
	ds_read2_b64 v[2:5], v11 offset0:200 offset1:202
	s_waitcnt lgkmcnt(1)
	v_lshlrev_b32_e32 v17, 16, v6
	v_and_b32_e32 v6, 0xffff0000, v6
	s_waitcnt lgkmcnt(0)
	v_lshlrev_b32_e32 v25, 16, v2
	v_and_b32_e32 v2, 0xffff0000, v2
	v_sub_f32_e32 v2, v2, v6
	v_lshlrev_b32_e32 v24, 16, v7
	v_and_b32_e32 v7, 0xffff0000, v7
	v_sub_f32_e32 v25, v25, v17
	s_waitcnt vmcnt(7)
	v_fmac_f32_e32 v6, v2, v161
	s_waitcnt vmcnt(6)
	v_mul_f32_e32 v2, v6, v165
	v_lshlrev_b32_e32 v6, 16, v3
	v_and_b32_e32 v3, 0xffff0000, v3
	v_fmac_f32_e32 v17, v160, v25
	v_sub_f32_e32 v6, v6, v24
	v_sub_f32_e32 v3, v3, v7
	v_mul_f32_e32 v12, v17, v164
	v_fmac_f32_e32 v24, v6, v162
	v_fmac_f32_e32 v7, v3, v163
	v_mul_f32_e32 v2, v2, v2
	v_mul_f32_e32 v6, v24, v166
	v_mul_f32_e32 v3, v7, v167
	v_fmac_f32_e32 v2, v12, v12
	v_fmac_f32_e32 v2, v6, v6
	v_fmac_f32_e32 v2, v3, v3
	v_lshlrev_b32_e32 v3, 16, v8
	v_and_b32_e32 v6, 0xffff0000, v8
	v_lshlrev_b32_e32 v7, 16, v9
	v_and_b32_e32 v8, 0xffff0000, v9
	v_lshlrev_b32_e32 v9, 16, v4
	v_and_b32_e32 v4, 0xffff0000, v4
	v_sub_f32_e32 v4, v4, v6
	v_sub_f32_e32 v9, v9, v3
	v_add_f32_e32 v2, v16, v2
	s_waitcnt vmcnt(5)
	v_fmac_f32_e32 v6, v4, v169
	s_waitcnt vmcnt(4)
	v_mul_f32_e32 v4, v6, v173
	v_lshlrev_b32_e32 v6, 16, v5
	v_fmac_f32_e32 v3, v168, v9
	v_sub_f32_e32 v6, v6, v7
	v_and_b32_e32 v5, 0xffff0000, v5
	v_mul_f32_e32 v3, v3, v172
	v_fmac_f32_e32 v7, v6, v170
	v_sub_f32_e32 v5, v5, v8
	v_mul_f32_e32 v4, v4, v4
	v_mul_f32_e32 v6, v7, v174
	v_fmac_f32_e32 v8, v5, v171
	v_fmac_f32_e32 v4, v3, v3
	v_mul_f32_e32 v5, v8, v175
	v_fmac_f32_e32 v4, v6, v6
	v_fmac_f32_e32 v4, v5, v5
	v_add_f32_e32 v20, v2, v4
	ds_read2_b64 v[6:9], v10 offset0:142 offset1:144
	ds_read2_b64 v[2:5], v11 offset0:204 offset1:206
	s_waitcnt lgkmcnt(1)
	v_lshlrev_b32_e32 v21, 16, v6
	v_and_b32_e32 v6, 0xffff0000, v6
	s_waitcnt lgkmcnt(0)
	v_lshlrev_b32_e32 v23, 16, v2
	v_and_b32_e32 v2, 0xffff0000, v2
	v_sub_f32_e32 v2, v2, v6
	v_lshlrev_b32_e32 v22, 16, v7
	v_and_b32_e32 v7, 0xffff0000, v7
	v_sub_f32_e32 v23, v23, v21
	s_waitcnt vmcnt(3)
	v_fmac_f32_e32 v6, v2, v177
	s_waitcnt vmcnt(2)
	v_mul_f32_e32 v2, v6, v181
	v_lshlrev_b32_e32 v6, 16, v3
	v_and_b32_e32 v3, 0xffff0000, v3
	v_fmac_f32_e32 v21, v176, v23
	v_sub_f32_e32 v6, v6, v22
	v_sub_f32_e32 v3, v3, v7
	v_mul_f32_e32 v10, v21, v180
	v_fmac_f32_e32 v22, v6, v178
	v_fmac_f32_e32 v7, v3, v179
	v_mul_f32_e32 v2, v2, v2
	v_mul_f32_e32 v6, v22, v182
	v_mul_f32_e32 v3, v7, v183
	v_fmac_f32_e32 v2, v10, v10
	v_fmac_f32_e32 v2, v6, v6
	v_fmac_f32_e32 v2, v3, v3
	v_lshlrev_b32_e32 v0, 16, v8
	v_and_b32_e32 v3, 0xffff0000, v8
	v_lshlrev_b32_e32 v8, 16, v4
	v_and_b32_e32 v4, 0xffff0000, v4
	v_sub_f32_e32 v4, v4, v3
	v_lshlrev_b32_e32 v6, 16, v9
	v_sub_f32_e32 v8, v8, v0
	v_and_b32_e32 v7, 0xffff0000, v9
	v_add_f32_e32 v2, v20, v2
	s_waitcnt vmcnt(1)
	v_fmac_f32_e32 v3, v4, v185
	v_lshlrev_b32_e32 v4, 16, v5
	v_fmac_f32_e32 v0, v184, v8
	s_waitcnt vmcnt(0)
	v_mul_f32_e32 v3, v3, v189
	v_sub_f32_e32 v4, v4, v6
	v_and_b32_e32 v5, 0xffff0000, v5
	v_mul_f32_e32 v0, v0, v188
	v_fmac_f32_e32 v6, v4, v186
	v_sub_f32_e32 v5, v5, v7
	v_mul_f32_e32 v3, v3, v3
	v_mul_f32_e32 v4, v6, v190
	v_fmac_f32_e32 v7, v5, v187
	v_fmac_f32_e32 v3, v0, v0
	v_mul_f32_e32 v5, v7, v191
	v_fmac_f32_e32 v3, v4, v4
	v_fmac_f32_e32 v3, v5, v5
	v_add_f32_e32 v0, v2, v3
	v_mov_b32_e32 v3, v0
	s_nop 1
	v_permlane32_swap_b32_e32 v0, v3
	v_add_f32_e32 v0, v0, v3
	v_cmp_gt_f32_e32 vcc, s0, v0
	v_mul_f32_e32 v3, 0x4f800000, v0
	s_mov_b32 s0, 0x1ffffc
	v_cndmask_b32_e32 v0, v0, v3, vcc
	v_sqrt_f32_e32 v3, v0
	v_and_b32_e32 v2, 0x7ff, v82
	v_add_u32_e32 v4, -1, v3
	v_fma_f32 v5, -v4, v3, v0
	v_cmp_ge_f32_e64 s[36:37], 0, v5
	v_add_u32_e32 v5, 1, v3
	s_nop 0
	v_cndmask_b32_e64 v4, v3, v4, s[36:37]
	v_fma_f32 v3, -v5, v3, v0
	v_cmp_lt_f32_e64 s[36:37], 0, v3
	s_nop 1
	v_cndmask_b32_e64 v3, v4, v5, s[36:37]
	v_mul_f32_e32 v4, 0x37800000, v3
	v_cndmask_b32_e32 v3, v3, v4, vcc
	v_cmp_class_f32_e32 vcc, v0, v224
	s_nop 1
	v_cndmask_b32_e32 v0, v3, v0, vcc
	v_max_f32_e32 v0, 0x2b8cbccc, v0
	v_div_scale_f32 v3, s[4:5], v0, v0, 1.0
	v_rcp_f32_e32 v4, v3
	s_nop 0
	v_fma_f32 v5, -v3, v4, 1.0
	v_fmac_f32_e32 v4, v5, v4
	v_div_scale_f32 v5, vcc, 1.0, v0, 1.0
	v_mul_f32_e32 v6, v5, v4
	v_fma_f32 v7, -v3, v6, v5
	v_fmac_f32_e32 v6, v7, v4
	v_fma_f32 v3, -v3, v6, v5
	v_div_fmas_f32 v3, v3, v4, v6
	v_div_fixup_f32 v123, v3, v0, 1.0
	v_lshrrev_b32_e32 v0, 9, v82
	v_and_or_b32 v0, v0, s0, v87
	v_lshl_or_b32 v0, v0, 11, v2
	v_mov_b64_e32 v[2:3], s[64:65]
	s_movk_i32 s0, 0x300
	v_mad_i64_i32 v[2:3], s[4:5], v0, s0, v[2:3]
	s_mov_b64 s[4:5], 0xc764500
	s_movk_i32 s0, 0x90
	v_lshl_add_u64 v[84:85], v[2:3], 0, s[4:5]
	v_mul_lo_u32 v3, v19, s0
	v_lshlrev_b32_e32 v2, 4, v118
	v_add3_u32 v86, 0, v3, v2
	v_mov_b32_e32 v3, v1
	v_lshl_add_u64 v[4:5], s[58:59], 0, v[2:3]
	s_mov_b64 s[4:5], 0x1288400
	v_lshl_add_u64 v[88:89], v[4:5], 0, s[4:5]
	v_lshl_add_u64 v[4:5], s[60:61], 0, v[2:3]
	s_mov_b64 s[4:5], 0x1290400
	v_lshl_add_u64 v[90:91], v[4:5], 0, s[4:5]
	v_lshlrev_b64 v[4:5], 9, v[82:83]
	v_lshl_add_u64 v[4:5], s[62:63], 0, v[4:5]
	s_mov_b64 s[4:5], 0xb724500
	v_lshl_add_u64 v[92:93], v[4:5], 0, s[4:5]
	v_lshlrev_b32_e32 v4, 7, v87
	v_mov_b32_e32 v5, v1
	v_lshl_add_u64 v[94:95], v[92:93], 0, v[4:5]
	s_movk_i32 s0, 0x180
	v_lshlrev_b32_e32 v4, 9, v18
	v_mad_u64_u32 v[96:97], s[4:5], v19, s0, v[86:87]
	v_lshl_add_u64 v[4:5], s[56:57], 0, v[4:5]
	v_lshlrev_b32_e32 v0, 3, v118
	v_lshl_add_u64 v[2:3], v[4:5], 0, v[2:3]
	s_mov_b64 s[4:5], 0x1298400
	v_lshl_add_u64 v[98:99], v[2:3], 0, s[4:5]
	v_lshl_add_u64 v[2:3], s[54:55], 0, v[0:1]
	s_mov_b64 s[4:5], 0x129c400
	v_lshl_add_u64 v[100:101], v[2:3], 0, s[4:5]
	v_lshlrev_b32_e32 v0, 6, v18
	v_lshlrev_b32_e32 v2, 5, v18
	v_lshl_or_b32 v0, v87, 12, v0
	v_lshl_or_b32 v2, v87, 11, v2
	s_mov_b32 s4, 0
	s_mov_b64 s[54:55], -1
	v_lshlrev_b32_e32 v97, 1, v0
	v_lshlrev_b32_e32 v124, 1, v2
	s_branch .LBB0_392

; DI float bflo(unsigned u) { return __uint_as_float(u << 16); }
; DI float bfhi(unsigned u) { return __uint_as_float(u & 0xffff0000u); }
; DI void scan_put(const uint4& g, int idx, float* dstbase) {
;   const int e0 = idx * 8; const int arr = (e0 % 384) >> 6;
;   float f[8] = {bflo(g.x), bfhi(g.x), bflo(g.y), bfhi(g.y), bflo(g.z), bfhi(g.z), bflo(g.w), bfhi(g.w)};
;   if (arr == 1) {
; #pragma unroll
;     for (int e = 0; e < 8; ++e) f[e] = 1.f - f[e];
;   }
;   *(float4*)(dstbase + e0) = make_float4(f[0], f[1], f[2], f[3]);
;   *(float4*)(dstbase + e0 + 4) = make_float4(f[4], f[5], f[6], f[7]);
; }
; DI void rwkv_scan(const Params& p, int item, char* smraw) {
;     ...
;       if (ch + 2 < 128) {
;         int nb = cur + 2; if (nb >= 3) nb -= 3;
;         float* dst = stage + nb * 16 * 384;
; #pragma unroll
;         for (int i = 0; i < 3; ++i) scan_put(g[i], st_ + 256 * i, dst);
;       }
;       if (ch + 3 < 128) {
;         const bf16_t* src = pr + (size_t)(ch + 3) * 16 * 384;
; #pragma unroll
;         for (int i = 0; i < 3; ++i) g[i] = *(const uint4*)(src + (size_t)(st_ + 256 * i) * 8);
;       }
.Lst_wd:
	s_and_b32 s1, s22, 3
	s_cmp_eq_u32 s1, 1
	s_cbranch_scc1 .Lst_put1
	s_cmp_eq_u32 s1, 2
	s_cbranch_scc1 .Lst_put2
	s_cmp_eq_u32 s1, 3
	s_cbranch_scc1 .Lst_put3
	v_lshlrev_b32_e32 v80, 16, v2
	v_and_b32_e32 v81, 0xffff0000, v2
	v_lshlrev_b32_e32 v82, 16, v3
	v_and_b32_e32 v83, 0xffff0000, v3
	v_lshlrev_b32_e32 v76, 16, v4
	v_and_b32_e32 v77, 0xffff0000, v4
	v_lshlrev_b32_e32 v78, 16, v5
	v_and_b32_e32 v79, 0xffff0000, v5
	v_cndmask_b32_e64 v84, 1.0, -1.0, s[38:39]
	v_cndmask_b32_e64 v86, 0, 1.0, s[38:39]
	v_lshl_add_u32 v61, v69, 2, s0
	v_pk_fma_f32 v[80:81], v[80:81], v[84:85], v[86:87] op_sel_hi:[1,0,0]
	v_pk_fma_f32 v[82:83], v[82:83], v[84:85], v[86:87] op_sel_hi:[1,0,0]
	v_pk_fma_f32 v[76:77], v[76:77], v[84:85], v[86:87] op_sel_hi:[1,0,0]
	v_pk_fma_f32 v[78:79], v[78:79], v[84:85], v[86:87] op_sel_hi:[1,0,0]
	ds_write_b128 v61, v[80:83]
	ds_write_b128 v61, v[76:79] offset:16
	v_lshlrev_b32_e32 v80, 16, v6
	v_and_b32_e32 v81, 0xffff0000, v6
	v_lshlrev_b32_e32 v82, 16, v7
	v_and_b32_e32 v83, 0xffff0000, v7
	v_lshlrev_b32_e32 v76, 16, v8
	v_and_b32_e32 v77, 0xffff0000, v8
	v_lshlrev_b32_e32 v78, 16, v9
	v_and_b32_e32 v79, 0xffff0000, v9
	v_cndmask_b32_e64 v84, 1.0, -1.0, s[40:41]
	v_cndmask_b32_e64 v86, 0, 1.0, s[40:41]
	v_lshl_add_u32 v61, v55, 2, s0
	v_pk_fma_f32 v[80:81], v[80:81], v[84:85], v[86:87] op_sel_hi:[1,0,0]
	v_pk_fma_f32 v[82:83], v[82:83], v[84:85], v[86:87] op_sel_hi:[1,0,0]
	v_pk_fma_f32 v[76:77], v[76:77], v[84:85], v[86:87] op_sel_hi:[1,0,0]
	v_pk_fma_f32 v[78:79], v[78:79], v[84:85], v[86:87] op_sel_hi:[1,0,0]
	ds_write_b128 v61, v[80:83]
	ds_write_b128 v61, v[76:79] offset:16
	v_lshlrev_b32_e32 v80, 16, v10
	v_and_b32_e32 v81, 0xffff0000, v10
	v_lshlrev_b32_e32 v82, 16, v11
	v_and_b32_e32 v83, 0xffff0000, v11
	v_lshlrev_b32_e32 v76, 16, v12
	v_and_b32_e32 v77, 0xffff0000, v12
	v_lshlrev_b32_e32 v78, 16, v13
	v_and_b32_e32 v79, 0xffff0000, v13
	v_cndmask_b32_e64 v84, 1.0, -1.0, s[42:43]
	v_cndmask_b32_e64 v86, 0, 1.0, s[42:43]
	v_lshl_add_u32 v61, v68, 2, s0
	v_pk_fma_f32 v[80:81], v[80:81], v[84:85], v[86:87] op_sel_hi:[1,0,0]
	v_pk_fma_f32 v[82:83], v[82:83], v[84:85], v[86:87] op_sel_hi:[1,0,0]
	v_pk_fma_f32 v[76:77], v[76:77], v[84:85], v[86:87] op_sel_hi:[1,0,0]
	v_pk_fma_f32 v[78:79], v[78:79], v[84:85], v[86:87] op_sel_hi:[1,0,0]
	ds_write_b128 v61, v[80:83]
	ds_write_b128 v61, v[76:79] offset:16
	s_cmpk_gt_u32 s22, 0x79
	s_cbranch_scc1 .LBB0_506
	s_add_u32 s98, s2, 0xc776500
	s_addc_u32 s99, s3, 0
	v_lshl_add_u64 v[166:167], v[58:59], 0, s[98:99]
	s_add_u32 s98, s98, 0x1000
	s_addc_u32 s99, s99, 0
	v_lshl_add_u64 v[168:169], v[58:59], 0, s[98:99]
	s_add_u32 s98, s98, 0x1000
	s_addc_u32 s99, s99, 0
	v_lshl_add_u64 v[170:171], v[58:59], 0, s[98:99]
	global_load_dwordx4 v[2:5], v[166:167], off
	global_load_dwordx4 v[6:9], v[168:169], off
	global_load_dwordx4 v[10:13], v[170:171], off
	s_branch .LBB0_506
.Lst_put1:
	v_lshlrev_b32_e32 v80, 16, v130
	v_and_b32_e32 v81, 0xffff0000, v130
	v_lshlrev_b32_e32 v82, 16, v131
	v_and_b32_e32 v83, 0xffff0000, v131
	v_lshlrev_b32_e32 v76, 16, v132
	v_and_b32_e32 v77, 0xffff0000, v132
	v_lshlrev_b32_e32 v78, 16, v133
	v_and_b32_e32 v79, 0xffff0000, v133
	v_cndmask_b32_e64 v84, 1.0, -1.0, s[38:39]
	v_cndmask_b32_e64 v86, 0, 1.0, s[38:39]
	v_lshl_add_u32 v61, v69, 2, s0
	v_pk_fma_f32 v[80:81], v[80:81], v[84:85], v[86:87] op_sel_hi:[1,0,0]
	v_pk_fma_f32 v[82:83], v[82:83], v[84:85], v[86:87] op_sel_hi:[1,0,0]
	v_pk_fma_f32 v[76:77], v[76:77], v[84:85], v[86:87] op_sel_hi:[1,0,0]
	v_pk_fma_f32 v[78:79], v[78:79], v[84:85], v[86:87] op_sel_hi:[1,0,0]
	ds_write_b128 v61, v[80:83]
	ds_write_b128 v61, v[76:79] offset:16
	v_lshlrev_b32_e32 v80, 16, v134
	v_and_b32_e32 v81, 0xffff0000, v134
	v_lshlrev_b32_e32 v82, 16, v135
	v_and_b32_e32 v83, 0xffff0000, v135
	v_lshlrev_b32_e32 v76, 16, v136
	v_and_b32_e32 v77, 0xffff0000, v136
	v_lshlrev_b32_e32 v78, 16, v137
	v_and_b32_e32 v79, 0xffff0000, v137
	v_cndmask_b32_e64 v84, 1.0, -1.0, s[40:41]
	v_cndmask_b32_e64 v86, 0, 1.0, s[40:41]
	v_lshl_add_u32 v61, v55, 2, s0
	v_pk_fma_f32 v[80:81], v[80:81], v[84:85], v[86:87] op_sel_hi:[1,0,0]
	v_pk_fma_f32 v[82:83], v[82:83], v[84:85], v[86:87] op_sel_hi:[1,0,0]
	v_pk_fma_f32 v[76:77], v[76:77], v[84:85], v[86:87] op_sel_hi:[1,0,0]
	v_pk_fma_f32 v[78:79], v[78:79], v[84:85], v[86:87] op_sel_hi:[1,0,0]
	ds_write_b128 v61, v[80:83]
	ds_write_b128 v61, v[76:79] offset:16
	v_lshlrev_b32_e32 v80, 16, v138
	v_and_b32_e32 v81, 0xffff0000, v138
	v_lshlrev_b32_e32 v82, 16, v139
	v_and_b32_e32 v83, 0xffff0000, v139
	v_lshlrev_b32_e32 v76, 16, v140
	v_and_b32_e32 v77, 0xffff0000, v140
	v_lshlrev_b32_e32 v78, 16, v141
	v_and_b32_e32 v79, 0xffff0000, v141
	v_cndmask_b32_e64 v84, 1.0, -1.0, s[42:43]
	v_cndmask_b32_e64 v86, 0, 1.0, s[42:43]
	v_lshl_add_u32 v61, v68, 2, s0
	v_pk_fma_f32 v[80:81], v[80:81], v[84:85], v[86:87] op_sel_hi:[1,0,0]
	v_pk_fma_f32 v[82:83], v[82:83], v[84:85], v[86:87] op_sel_hi:[1,0,0]
	v_pk_fma_f32 v[76:77], v[76:77], v[84:85], v[86:87] op_sel_hi:[1,0,0]
	v_pk_fma_f32 v[78:79], v[78:79], v[84:85], v[86:87] op_sel_hi:[1,0,0]
	ds_write_b128 v61, v[80:83]
	ds_write_b128 v61, v[76:79] offset:16
	s_cmpk_gt_u32 s22, 0x79
	s_cbranch_scc1 .LBB0_506
	s_add_u32 s98, s2, 0xc776500
	s_addc_u32 s99, s3, 0
	v_lshl_add_u64 v[166:167], v[58:59], 0, s[98:99]
	s_add_u32 s98, s98, 0x1000
	s_addc_u32 s99, s99, 0
	v_lshl_add_u64 v[168:169], v[58:59], 0, s[98:99]
	s_add_u32 s98, s98, 0x1000
	s_addc_u32 s99, s99, 0
	v_lshl_add_u64 v[170:171], v[58:59], 0, s[98:99]
	global_load_dwordx4 v[130:133], v[166:167], off
	global_load_dwordx4 v[134:137], v[168:169], off
	global_load_dwordx4 v[138:141], v[170:171], off
	s_branch .LBB0_506
; DI float bflo(unsigned u) { return __uint_as_float(u << 16); }
; DI float bfhi(unsigned u) { return __uint_as_float(u & 0xffff0000u); }
; DI void scan_put(const uint4& g, int idx, float* dstbase) {
;   const int e0 = idx * 8; const int arr = (e0 % 384) >> 6;
;   float f[8] = {bflo(g.x), bfhi(g.x), bflo(g.y), bfhi(g.y), bflo(g.z), bfhi(g.z), bflo(g.w), bfhi(g.w)};
;   if (arr == 1) {
; #pragma unroll
;     for (int e = 0; e < 8; ++e) f[e] = 1.f - f[e];
;   }
;   *(float4*)(dstbase + e0) = make_float4(f[0], f[1], f[2], f[3]);
;   *(float4*)(dstbase + e0 + 4) = make_float4(f[4], f[5], f[6], f[7]);
; }
; DI void rwkv_scan(const Params& p, int item, char* smraw) {
;     ...
;       if (ch + 2 < 128) {
;         int nb = cur + 2; if (nb >= 3) nb -= 3;
;         float* dst = stage + nb * 16 * 384;
; #pragma unroll
;         for (int i = 0; i < 3; ++i) scan_put(g[i], st_ + 256 * i, dst);
;       }
;       if (ch + 3 < 128) {
;         const bf16_t* src = pr + (size_t)(ch + 3) * 16 * 384;
; #pragma unroll
;         for (int i = 0; i < 3; ++i) g[i] = *(const uint4*)(src + (size_t)(st_ + 256 * i) * 8);
;       }
.Lst_put2:
	v_lshlrev_b32_e32 v80, 16, v142
	v_and_b32_e32 v81, 0xffff0000, v142
	v_lshlrev_b32_e32 v82, 16, v143
	v_and_b32_e32 v83, 0xffff0000, v143
	v_lshlrev_b32_e32 v76, 16, v144
	v_and_b32_e32 v77, 0xffff0000, v144
	v_lshlrev_b32_e32 v78, 16, v145
	v_and_b32_e32 v79, 0xffff0000, v145
	v_cndmask_b32_e64 v84, 1.0, -1.0, s[38:39]
	v_cndmask_b32_e64 v86, 0, 1.0, s[38:39]
	v_lshl_add_u32 v61, v69, 2, s0
	v_pk_fma_f32 v[80:81], v[80:81], v[84:85], v[86:87] op_sel_hi:[1,0,0]
	v_pk_fma_f32 v[82:83], v[82:83], v[84:85], v[86:87] op_sel_hi:[1,0,0]
	v_pk_fma_f32 v[76:77], v[76:77], v[84:85], v[86:87] op_sel_hi:[1,0,0]
	v_pk_fma_f32 v[78:79], v[78:79], v[84:85], v[86:87] op_sel_hi:[1,0,0]
	ds_write_b128 v61, v[80:83]
	ds_write_b128 v61, v[76:79] offset:16
	v_lshlrev_b32_e32 v80, 16, v146
	v_and_b32_e32 v81, 0xffff0000, v146
	v_lshlrev_b32_e32 v82, 16, v147
	v_and_b32_e32 v83, 0xffff0000, v147
	v_lshlrev_b32_e32 v76, 16, v148
	v_and_b32_e32 v77, 0xffff0000, v148
	v_lshlrev_b32_e32 v78, 16, v149
	v_and_b32_e32 v79, 0xffff0000, v149
	v_cndmask_b32_e64 v84, 1.0, -1.0, s[40:41]
	v_cndmask_b32_e64 v86, 0, 1.0, s[40:41]
	v_lshl_add_u32 v61, v55, 2, s0
	v_pk_fma_f32 v[80:81], v[80:81], v[84:85], v[86:87] op_sel_hi:[1,0,0]
	v_pk_fma_f32 v[82:83], v[82:83], v[84:85], v[86:87] op_sel_hi:[1,0,0]
	v_pk_fma_f32 v[76:77], v[76:77], v[84:85], v[86:87] op_sel_hi:[1,0,0]
	v_pk_fma_f32 v[78:79], v[78:79], v[84:85], v[86:87] op_sel_hi:[1,0,0]
	ds_write_b128 v61, v[80:83]
	ds_write_b128 v61, v[76:79] offset:16
	v_lshlrev_b32_e32 v80, 16, v150
	v_and_b32_e32 v81, 0xffff0000, v150
	v_lshlrev_b32_e32 v82, 16, v151
	v_and_b32_e32 v83, 0xffff0000, v151
	v_lshlrev_b32_e32 v76, 16, v152
	v_and_b32_e32 v77, 0xffff0000, v152
	v_lshlrev_b32_e32 v78, 16, v153
	v_and_b32_e32 v79, 0xffff0000, v153
	v_cndmask_b32_e64 v84, 1.0, -1.0, s[42:43]
	v_cndmask_b32_e64 v86, 0, 1.0, s[42:43]
	v_lshl_add_u32 v61, v68, 2, s0
	v_pk_fma_f32 v[80:81], v[80:81], v[84:85], v[86:87] op_sel_hi:[1,0,0]
	v_pk_fma_f32 v[82:83], v[82:83], v[84:85], v[86:87] op_sel_hi:[1,0,0]
	v_pk_fma_f32 v[76:77], v[76:77], v[84:85], v[86:87] op_sel_hi:[1,0,0]
	v_pk_fma_f32 v[78:79], v[78:79], v[84:85], v[86:87] op_sel_hi:[1,0,0]
	ds_write_b128 v61, v[80:83]
	ds_write_b128 v61, v[76:79] offset:16
	s_cmpk_gt_u32 s22, 0x79
	s_cbranch_scc1 .LBB0_506
	s_add_u32 s98, s2, 0xc776500
	s_addc_u32 s99, s3, 0
	v_lshl_add_u64 v[166:167], v[58:59], 0, s[98:99]
	s_add_u32 s98, s98, 0x1000
	s_addc_u32 s99, s99, 0
	v_lshl_add_u64 v[168:169], v[58:59], 0, s[98:99]
	s_add_u32 s98, s98, 0x1000
	s_addc_u32 s99, s99, 0
	v_lshl_add_u64 v[170:171], v[58:59], 0, s[98:99]
	global_load_dwordx4 v[142:145], v[166:167], off
	global_load_dwordx4 v[146:149], v[168:169], off
	global_load_dwordx4 v[150:153], v[170:171], off
	s_branch .LBB0_506
.Lst_put3:
	v_lshlrev_b32_e32 v80, 16, v154
	v_and_b32_e32 v81, 0xffff0000, v154
	v_lshlrev_b32_e32 v82, 16, v155
	v_and_b32_e32 v83, 0xffff0000, v155
	v_lshlrev_b32_e32 v76, 16, v156
	v_and_b32_e32 v77, 0xffff0000, v156
	v_lshlrev_b32_e32 v78, 16, v157
	v_and_b32_e32 v79, 0xffff0000, v157
	v_cndmask_b32_e64 v84, 1.0, -1.0, s[38:39]
	v_cndmask_b32_e64 v86, 0, 1.0, s[38:39]
	v_lshl_add_u32 v61, v69, 2, s0
	v_pk_fma_f32 v[80:81], v[80:81], v[84:85], v[86:87] op_sel_hi:[1,0,0]
	v_pk_fma_f32 v[82:83], v[82:83], v[84:85], v[86:87] op_sel_hi:[1,0,0]
	v_pk_fma_f32 v[76:77], v[76:77], v[84:85], v[86:87] op_sel_hi:[1,0,0]
	v_pk_fma_f32 v[78:79], v[78:79], v[84:85], v[86:87] op_sel_hi:[1,0,0]
	ds_write_b128 v61, v[80:83]
	ds_write_b128 v61, v[76:79] offset:16
	v_lshlrev_b32_e32 v80, 16, v158
	v_and_b32_e32 v81, 0xffff0000, v158
	v_lshlrev_b32_e32 v82, 16, v159
	v_and_b32_e32 v83, 0xffff0000, v159
	v_lshlrev_b32_e32 v76, 16, v160
	v_and_b32_e32 v77, 0xffff0000, v160
	v_lshlrev_b32_e32 v78, 16, v161
	v_and_b32_e32 v79, 0xffff0000, v161
	v_cndmask_b32_e64 v84, 1.0, -1.0, s[40:41]
	v_cndmask_b32_e64 v86, 0, 1.0, s[40:41]
	v_lshl_add_u32 v61, v55, 2, s0
	v_pk_fma_f32 v[80:81], v[80:81], v[84:85], v[86:87] op_sel_hi:[1,0,0]
	v_pk_fma_f32 v[82:83], v[82:83], v[84:85], v[86:87] op_sel_hi:[1,0,0]
	v_pk_fma_f32 v[76:77], v[76:77], v[84:85], v[86:87] op_sel_hi:[1,0,0]
	v_pk_fma_f32 v[78:79], v[78:79], v[84:85], v[86:87] op_sel_hi:[1,0,0]
	ds_write_b128 v61, v[80:83]
	ds_write_b128 v61, v[76:79] offset:16
	v_lshlrev_b32_e32 v80, 16, v162
	v_and_b32_e32 v81, 0xffff0000, v162
	v_lshlrev_b32_e32 v82, 16, v163
	v_and_b32_e32 v83, 0xffff0000, v163
	v_lshlrev_b32_e32 v76, 16, v164
	v_and_b32_e32 v77, 0xffff0000, v164
	v_lshlrev_b32_e32 v78, 16, v165
	v_and_b32_e32 v79, 0xffff0000, v165
	v_cndmask_b32_e64 v84, 1.0, -1.0, s[42:43]
	v_cndmask_b32_e64 v86, 0, 1.0, s[42:43]
	v_lshl_add_u32 v61, v68, 2, s0
	v_pk_fma_f32 v[80:81], v[80:81], v[84:85], v[86:87] op_sel_hi:[1,0,0]
	v_pk_fma_f32 v[82:83], v[82:83], v[84:85], v[86:87] op_sel_hi:[1,0,0]
	v_pk_fma_f32 v[76:77], v[76:77], v[84:85], v[86:87] op_sel_hi:[1,0,0]
	v_pk_fma_f32 v[78:79], v[78:79], v[84:85], v[86:87] op_sel_hi:[1,0,0]
	ds_write_b128 v61, v[80:83]
	ds_write_b128 v61, v[76:79] offset:16
	s_cmpk_gt_u32 s22, 0x79
	s_cbranch_scc1 .LBB0_506
	s_add_u32 s98, s2, 0xc776500
	s_addc_u32 s99, s3, 0
	v_lshl_add_u64 v[166:167], v[58:59], 0, s[98:99]
	s_add_u32 s98, s98, 0x1000
	s_addc_u32 s99, s99, 0
	v_lshl_add_u64 v[168:169], v[58:59], 0, s[98:99]
	s_add_u32 s98, s98, 0x1000
	s_addc_u32 s99, s99, 0
	v_lshl_add_u64 v[170:171], v[58:59], 0, s[98:99]
	global_load_dwordx4 v[154:157], v[166:167], off
	global_load_dwordx4 v[158:161], v[168:169], off
	global_load_dwordx4 v[162:165], v[170:171], off
